# v12 + differential-attention mixer: O accumulators kept in place in both tile variants (removed 32-64 v_mov_b64 register copies per tile)
# speedup vs baseline: 1.0065x; 1.0065x over previous
.LBB0_93:
	s_mul_i32 s0, s44, 0xac00
	s_sub_i32 s27, s45, 64
	s_add_i32 s48, s0, 0
	s_cmp_gt_i32 s27, s47
	s_cselect_b64 s[0:1], -1, 0
	s_cmp_lt_i32 s27, s46
	v_sub_f32_e32 v0, v230, v239
	s_cselect_b64 s[42:43], -1, 0
	v_cndmask_b32_e64 v66, v0, -v239, s[42:43]
	s_and_b64 s[42:43], s[0:1], s[42:43]
	s_andn2_b64 vcc, exec, s[42:43]
	v_add_u32_e32 v242, s48, v237
	v_add_u32_e32 v241, s48, v238
	s_cbranch_vccz .LBB0_95
	v_sub_f32_e32 v0, v229, v239
	ds_read_b128 v[100:103], v242
	ds_read_b128 v[104:107], v242 offset:32
	ds_read_b128 v[108:111], v242 offset:64
	v_cndmask_b32_e64 v68, v0, v66, s[0:1]
	v_mov_b32_e32 v69, v68
	v_mov_b32_e32 v70, v68
	v_mov_b32_e32 v71, v68
	v_mov_b32_e32 v72, v68
	v_mov_b32_e32 v73, v68
	v_mov_b32_e32 v74, v68
	v_mov_b32_e32 v75, v68
	v_mov_b32_e32 v76, v68
	v_mov_b32_e32 v77, v68
	v_mov_b32_e32 v78, v68
	v_mov_b32_e32 v79, v68
	v_mov_b32_e32 v80, v68
	v_mov_b32_e32 v81, v68
	v_mov_b32_e32 v82, v68
	v_mov_b32_e32 v83, v68
	ds_read_b128 v[112:115], v242 offset:96
	s_waitcnt lgkmcnt(3)
	v_mfma_f32_32x32x16_bf16 v[84:99], v[100:103], v[164:167], v[68:83]
	ds_read_b128 v[116:119], v242 offset:8704
	s_waitcnt lgkmcnt(3)
	v_mfma_f32_32x32x16_bf16 v[84:99], v[104:107], v[168:171], v[84:99]
	ds_read_b128 v[120:123], v242 offset:8736
	s_waitcnt lgkmcnt(3)
	v_mfma_f32_32x32x16_bf16 v[84:99], v[108:111], v[172:175], v[84:99]
	ds_read_b128 v[244:247], v241 offset:31232
	ds_read_b128 v[104:107], v242 offset:8768
	s_waitcnt lgkmcnt(4)
	v_mfma_f32_32x32x16_bf16 v[84:99], v[112:115], v[176:179], v[84:99]
	ds_read_b128 v[100:103], v242 offset:8800
	s_waitcnt lgkmcnt(4)
	v_mfma_f32_32x32x16_bf16 v[68:83], v[116:119], v[164:167], v[68:83]
	s_nop 8
	v_max_f32_e32 v0, v84, v85
	v_exp_f32_e32 v67, v84
	v_exp_f32_e32 v84, v85
	s_nop 0
	v_add_f32_e32 v85, v67, v84
	v_cvt_pk_bf16_f32 v180, v67, v84
	v_max_f32_e32 v67, v86, v87
	v_max3_f32 v67, v0, s86, v67
	v_exp_f32_e32 v84, v86
	v_exp_f32_e32 v0, v87
	s_nop 0
	v_pk_add_f32 v[86:87], v[84:85], v[0:1]
	s_nop 0
	v_pk_add_f32 v[86:87], v[86:87], v[86:87] op_sel_hi:[0,1]
	v_cvt_pk_bf16_f32 v181, v84, v0
	ds_read_b128 v[108:111], v241 offset:17408
	v_max_f32_e32 v0, v88, v89
	v_exp_f32_e32 v84, v88
	v_exp_f32_e32 v86, v89
	s_waitcnt lgkmcnt(4)
	v_mfma_f32_32x32x16_bf16 v[68:83], v[120:123], v[168:171], v[68:83]
	v_add_f32_e32 v85, v84, v86
	v_cvt_pk_bf16_f32 v182, v84, v86
	v_max_f32_e32 v84, v90, v91
	v_max3_f32 v0, v67, v0, v84
	v_exp_f32_e32 v84, v90
	v_exp_f32_e32 v86, v91
	s_nop 0
	v_pk_add_f32 v[88:89], v[84:85], v[86:87]
	s_nop 0
	v_pk_add_f32 v[88:89], v[88:89], v[88:89] op_sel_hi:[0,1]
	v_cvt_pk_bf16_f32 v183, v84, v86
	ds_read_b128 v[116:119], v241 offset:22016
	v_max_f32_e32 v67, v92, v93
	v_exp_f32_e32 v84, v92
	v_exp_f32_e32 v86, v93
	v_exp_f32_e32 v88, v95
	s_waitcnt lgkmcnt(3)
	v_mfma_f32_32x32x16_bf16 v[68:83], v[104:107], v[172:175], v[68:83]
	v_add_f32_e32 v85, v84, v86
	v_cvt_pk_bf16_f32 v184, v84, v86
	v_max_f32_e32 v84, v94, v95
	v_max3_f32 v0, v0, v67, v84
	v_exp_f32_e32 v84, v94
	s_nop 0
	v_pk_add_f32 v[86:87], v[84:85], v[88:89]
	s_nop 0
	v_pk_add_f32 v[86:87], v[86:87], v[86:87] op_sel_hi:[0,1]
	v_cvt_pk_bf16_f32 v185, v84, v88
	ds_read_b128 v[132:135], v241 offset:26624
	v_max_f32_e32 v67, v96, v97
	v_exp_f32_e32 v84, v96
	v_exp_f32_e32 v86, v97
	s_waitcnt lgkmcnt(3)
	v_mfma_f32_32x32x16_bf16 v[68:83], v[100:103], v[176:179], v[68:83]
	v_add_f32_e32 v85, v84, v86
	v_cvt_pk_bf16_f32 v186, v84, v86
	v_max_f32_e32 v84, v98, v99
	v_max3_f32 v0, v0, v67, v84
	v_exp_f32_e32 v84, v98
	v_exp_f32_e32 v86, v99
	s_nop 0
	v_pk_add_f32 v[88:89], v[84:85], v[86:87]
	s_nop 0
	v_pk_add_f32 v[120:121], v[88:89], v[88:89] op_sel_hi:[0,1]
	v_cvt_pk_bf16_f32 v187, v84, v86
	ds_read_b128 v[188:191], v241 offset:17440
	s_waitcnt lgkmcnt(3)
	v_mfma_f32_32x32x16_bf16 v[34:49], v[108:111], v[180:183], v[34:49]
	v_max_f32_e32 v67, v69, v69
	v_max_f32_e32 v100, v68, v68
	v_exp_f32_e32 v68, v68
	v_exp_f32_e32 v69, v69
	v_max_f32_e32 v67, v100, v67
	v_add_f32_e32 v123, v68, v69
	v_cvt_pk_bf16_f32 v68, v68, v69
	ds_read_b128 v[214:217], v241 offset:22048
	s_waitcnt lgkmcnt(3)
	v_mfma_f32_32x32x16_bf16 v[18:33], v[116:119], v[180:183], v[18:33]
	v_exp_f32_e32 v120, v70
	v_exp_f32_e32 v122, v71
	v_max_f32_e32 v69, v70, v71
	v_pk_add_f32 v[70:71], v[120:121], v[122:123]
	v_max3_f32 v0, v0, v67, v69
	v_pk_add_f32 v[248:249], v[70:71], v[70:71] op_sel_hi:[0,1]
	v_cvt_pk_bf16_f32 v69, v120, v122
	ds_read_b128 v[218:221], v241 offset:26656
	s_waitcnt lgkmcnt(3)
	v_mfma_f32_32x32x16_bf16 v[2:17], v[132:135], v[180:183], v[2:17]
	v_max_f32_e32 v67, v72, v73
	v_exp_f32_e32 v70, v72
	v_exp_f32_e32 v71, v73
	s_nop 0
	v_add_f32_e32 v73, v70, v71
	v_cvt_pk_bf16_f32 v70, v70, v71
	v_mfma_f32_32x32x16_bf16 v[50:65], v[244:247], v[180:183], v[50:65]
	v_max_f32_e32 v71, v74, v75
	v_exp_f32_e32 v72, v74
	v_exp_f32_e32 v248, v75
	v_max3_f32 v0, v0, v67, v71
	v_pk_add_f32 v[74:75], v[72:73], v[248:249]
	s_nop 0
	v_pk_add_f32 v[244:245], v[74:75], v[74:75] op_sel_hi:[0,1]
	v_cvt_pk_bf16_f32 v71, v72, v248
	ds_read_b128 v[72:75], v241 offset:31264
	s_waitcnt lgkmcnt(3)
	v_mfma_f32_32x32x16_bf16 v[34:49], v[188:191], v[184:187], v[34:49]
	v_max_f32_e32 v67, v77, v77
	v_max_f32_e32 v180, v76, v76
	v_exp_f32_e32 v76, v76
	v_exp_f32_e32 v77, v77
	v_max_f32_e32 v67, v180, v67
	v_add_f32_e32 v189, v76, v77
	v_cvt_pk_bf16_f32 v76, v76, v77
	ds_read_b128 v[180:183], v241 offset:17472
	s_waitcnt lgkmcnt(3)
	v_mfma_f32_32x32x16_bf16 v[18:33], v[214:217], v[184:187], v[18:33]
	v_max_f32_e32 v77, v78, v79
	v_exp_f32_e32 v188, v78
	v_exp_f32_e32 v244, v79
	v_max3_f32 v0, v0, v67, v77
	v_pk_add_f32 v[78:79], v[188:189], v[244:245]
	s_nop 0
	v_pk_add_f32 v[246:247], v[78:79], v[78:79] op_sel_hi:[0,1]
	v_cvt_pk_bf16_f32 v77, v188, v244
	ds_read_b128 v[188:191], v241 offset:22080
	s_waitcnt lgkmcnt(3)
	v_mfma_f32_32x32x16_bf16 v[2:17], v[218:221], v[184:187], v[2:17]
	v_max_f32_e32 v67, v80, v81
	v_exp_f32_e32 v78, v80
	v_exp_f32_e32 v79, v81
	s_nop 0
	v_add_f32_e32 v81, v78, v79
	v_cvt_pk_bf16_f32 v78, v78, v79
	ds_read_b128 v[214:217], v241 offset:26688
	s_waitcnt lgkmcnt(3)
	v_mfma_f32_32x32x16_bf16 v[50:65], v[72:75], v[184:187], v[50:65]
	v_exp_f32_e32 v80, v82
	v_exp_f32_e32 v246, v83
	v_max_f32_e32 v220, v82, v83
	v_pk_add_f32 v[218:219], v[80:81], v[246:247]
	v_cvt_pk_bf16_f32 v79, v80, v246
	ds_read_b128 v[72:75], v241 offset:31296
	ds_read_b128 v[80:83], v241 offset:17504
	s_waitcnt lgkmcnt(4)
	v_mfma_f32_32x32x16_bf16 v[34:49], v[180:183], v[68:71], v[34:49]
	ds_read_b128 v[180:183], v241 offset:22112
	s_waitcnt lgkmcnt(4)
	v_mfma_f32_32x32x16_bf16 v[18:33], v[188:191], v[68:71], v[18:33]
	ds_read_b128 v[184:187], v241 offset:26720
	s_waitcnt lgkmcnt(4)
	v_mfma_f32_32x32x16_bf16 v[2:17], v[214:217], v[68:71], v[2:17]
	s_waitcnt lgkmcnt(3)
	v_mfma_f32_32x32x16_bf16 v[50:65], v[72:75], v[68:71], v[50:65]
	ds_read_b128 v[68:71], v241 offset:31328
	s_waitcnt lgkmcnt(3)
	v_mfma_f32_32x32x16_bf16 v[34:49], v[80:83], v[76:79], v[34:49]
	s_waitcnt lgkmcnt(2)
	v_mfma_f32_32x32x16_bf16 v[18:33], v[180:183], v[76:79], v[18:33]
	s_waitcnt lgkmcnt(1)
	v_mfma_f32_32x32x16_bf16 v[2:17], v[184:187], v[76:79], v[2:17]
	s_waitcnt lgkmcnt(0)
	v_mfma_f32_32x32x16_bf16 v[50:65], v[68:71], v[76:79], v[50:65]
	v_max3_f32 v67, v0, v67, v220
	ds_bpermute_b32 v68, v195, v67
	v_add_f32_e32 v0, v218, v219
	v_add_f32_e32 v0, v240, v0
	s_waitcnt lgkmcnt(0)
	v_max_f32_e32 v68, v68, v68
	v_max_f32_e32 v67, v67, v68
	v_cmp_lt_f32_e32 vcc, s87, v67
	s_cmp_lg_u64 vcc, 0
	s_cselect_b64 s[0:1], -1, 0
	s_cbranch_execz .LBB0_96
	s_branch .LBB0_97

.LBB0_96:
	v_lshl_add_u64 v[138:139], s[88:89], 0, v[204:205]
	ds_read_b128 v[98:101], v242
	ds_read_b128 v[102:105], v242 offset:32
	ds_read_b128 v[106:109], v242 offset:64
	global_load_dwordx4 v[110:113], v[138:139], off offset:-128
	global_load_dwordx4 v[114:117], v[138:139], off offset:-112
	v_mov_b32_e32 v67, v66
	v_mov_b32_e32 v68, v66
	v_mov_b32_e32 v69, v66
	v_mov_b32_e32 v70, v66
	v_mov_b32_e32 v71, v66
	v_mov_b32_e32 v72, v66
	v_mov_b32_e32 v73, v66
	v_mov_b32_e32 v74, v66
	v_mov_b32_e32 v75, v66
	v_mov_b32_e32 v76, v66
	v_mov_b32_e32 v77, v66
	v_mov_b32_e32 v78, v66
	v_mov_b32_e32 v79, v66
	v_mov_b32_e32 v80, v66
	v_mov_b32_e32 v81, v66
	global_load_dwordx4 v[122:125], v[138:139], off offset:-64
	s_waitcnt lgkmcnt(2)
	v_mfma_f32_32x32x16_bf16 v[82:97], v[98:101], v[164:167], v[66:81]
	ds_read_b128 v[98:101], v242 offset:96
	ds_read_b128 v[118:121], v242 offset:8704
	s_waitcnt lgkmcnt(3)
	v_mfma_f32_32x32x16_bf16 v[82:97], v[102:105], v[168:171], v[82:97]
	ds_read_b128 v[126:129], v242 offset:8736
	s_waitcnt lgkmcnt(3)
	v_mfma_f32_32x32x16_bf16 v[82:97], v[106:109], v[172:175], v[82:97]
	s_waitcnt lgkmcnt(2)
	v_mfma_f32_32x32x16_bf16 v[82:97], v[98:101], v[176:179], v[82:97]
	global_load_dwordx4 v[130:133], v[138:139], off offset:-48
	global_load_dwordx4 v[134:137], v[138:139], off
	global_load_dwordx4 v[106:109], v[138:139], off offset:16
	global_load_dwordx4 v[98:101], v[138:139], off offset:80
	global_load_dwordx4 v[102:105], v[138:139], off offset:64
	ds_read_b128 v[138:141], v242 offset:8768
	ds_read_b128 v[142:145], v242 offset:8800
	s_waitcnt vmcnt(7)
	s_nop 3
	v_add_f32_e32 v0, v110, v82
	v_add_f32_e32 v82, v111, v83
	v_add_f32_e32 v83, v112, v84
	v_add_f32_e32 v85, v113, v85
	v_max_f32_e32 v110, v0, v82
	v_exp_f32_e32 v111, v0
	v_exp_f32_e32 v82, v82
	v_exp_f32_e32 v84, v83
	v_exp_f32_e32 v0, v85
	s_waitcnt lgkmcnt(3)
	v_mfma_f32_32x32x16_bf16 v[66:81], v[118:121], v[164:167], v[66:81]
	v_max_f32_e32 v112, v83, v85
	v_add_f32_e32 v85, v111, v82
	v_cvt_pk_bf16_f32 v83, v84, v0
	v_add_f32_e64 v84, v84, v0
	v_add_f32_e64 v85, v85, v1
	v_max3_f32 v120, v110, s86, v112
	v_cvt_pk_bf16_f32 v82, v111, v82
	v_pk_add_f32 v[118:119], v[84:85], v[84:85] op_sel_hi:[0,1]
	ds_read_b128 v[110:113], v241 offset:17408
	s_waitcnt vmcnt(6)
	v_add_f32_e32 v0, v114, v86
	v_add_f32_e32 v84, v115, v87
	v_add_f32_e32 v85, v116, v88
	v_add_f32_e32 v87, v117, v89
	v_max_f32_e32 v88, v0, v84
	v_exp_f32_e32 v0, v0
	v_exp_f32_e32 v84, v84
	v_exp_f32_e32 v86, v85
	v_exp_f32_e32 v118, v87
	s_waitcnt lgkmcnt(3)
	v_mfma_f32_32x32x16_bf16 v[66:81], v[126:129], v[168:171], v[66:81]
	v_max_f32_e32 v89, v85, v87
	v_add_f32_e32 v87, v0, v84
	v_cvt_pk_bf16_f32 v85, v86, v118
	v_add_f32_e64 v86, v86, v118
	v_add_f32_e64 v87, v87, v119
	v_max3_f32 v116, v120, v88, v89
	v_cvt_pk_bf16_f32 v84, v0, v84
	v_pk_add_f32 v[114:115], v[86:87], v[86:87] op_sel_hi:[0,1]
	ds_read_b128 v[86:89], v241 offset:22016
	s_waitcnt vmcnt(5)
	v_add_f32_e32 v0, v122, v90
	v_add_f32_e32 v90, v123, v91
	v_add_f32_e32 v91, v124, v92
	v_add_f32_e32 v93, v125, v93
	v_max_f32_e32 v117, v0, v90
	v_exp_f32_e32 v0, v0
	v_exp_f32_e32 v90, v90
	v_exp_f32_e32 v92, v91
	v_exp_f32_e32 v114, v93
	v_max_f32_e32 v118, v91, v93
	v_add_f32_e32 v93, v0, v90
	v_max3_f32 v120, v116, v117, v118
	v_cvt_pk_bf16_f32 v91, v92, v114
	v_pk_add_f32 v[92:93], v[92:93], v[114:115]
	ds_read_b128 v[114:117], v241 offset:26624
	s_waitcnt lgkmcnt(4)
	v_mfma_f32_32x32x16_bf16 v[66:81], v[138:141], v[172:175], v[66:81]
	v_cvt_pk_bf16_f32 v90, v0, v90
	v_add_f32_e64 v118, v92, v92
	v_add_f32_e64 v119, v92, v93
	s_waitcnt vmcnt(4)
	v_add_f32_e32 v0, v130, v94
	v_add_f32_e32 v92, v131, v95
	v_add_f32_e32 v93, v132, v96
	v_add_f32_e32 v95, v133, v97
	v_max_f32_e32 v96, v0, v92
	s_waitcnt lgkmcnt(3)
	v_mfma_f32_32x32x16_bf16 v[66:81], v[142:145], v[176:179], v[66:81]
	v_exp_f32_e32 v0, v0
	v_exp_f32_e32 v92, v92
	v_exp_f32_e32 v94, v93
	v_exp_f32_e32 v118, v95
	v_max_f32_e32 v97, v93, v95
	v_add_f32_e32 v95, v0, v92
	v_max3_f32 v126, v120, v96, v97
	v_cvt_pk_bf16_f32 v93, v94, v118
	v_pk_add_f32 v[94:95], v[94:95], v[118:119]
	v_cvt_pk_bf16_f32 v92, v0, v92
	v_pk_add_f32 v[122:123], v[94:95], v[94:95] op_sel_hi:[0,1]
	ds_read_b128 v[94:97], v241 offset:31232
	ds_read_b128 v[118:121], v241 offset:17440
	s_waitcnt lgkmcnt(4)
	v_mfma_f32_32x32x16_bf16 v[34:49], v[110:113], v[82:85], v[34:49]
	s_waitcnt vmcnt(3)
	v_add_f32_e32 v0, v134, v66
	v_add_f32_e32 v66, v135, v67
	v_exp_f32_e32 v67, v0
	v_exp_f32_e32 v110, v66
	v_max_f32_e32 v0, v0, v66
	v_add_f32_e32 v125, v67, v110
	v_cvt_pk_bf16_f32 v66, v67, v110
	ds_read_b128 v[110:113], v241 offset:22048
	s_waitcnt lgkmcnt(4)
	v_mfma_f32_32x32x16_bf16 v[18:33], v[86:89], v[82:85], v[18:33]
	v_add_f32_e32 v67, v136, v68
	v_add_f32_e32 v68, v137, v69
	v_exp_f32_e32 v122, v67
	v_exp_f32_e32 v124, v68
	v_max_f32_e32 v67, v67, v68
	v_max3_f32 v0, v126, v0, v67
	v_pk_add_f32 v[68:69], v[122:123], v[124:125]
	s_nop 0
	v_pk_add_f32 v[126:127], v[68:69], v[68:69] op_sel_hi:[0,1]
	v_cvt_pk_bf16_f32 v67, v122, v124
	ds_read_b128 v[86:89], v241 offset:26656
	s_waitcnt lgkmcnt(4)
	v_mfma_f32_32x32x16_bf16 v[2:17], v[114:117], v[82:85], v[2:17]
	s_waitcnt vmcnt(2)
	v_add_f32_e32 v68, v106, v70
	v_add_f32_e32 v69, v107, v71
	v_exp_f32_e32 v70, v68
	v_exp_f32_e32 v106, v69
	v_max_f32_e32 v69, v68, v69
	v_add_f32_e32 v71, v70, v106
	v_cvt_pk_bf16_f32 v68, v70, v106
	ds_read_b128 v[114:117], v241 offset:31264
	s_waitcnt lgkmcnt(4)
	v_mfma_f32_32x32x16_bf16 v[50:65], v[94:97], v[82:85], v[50:65]
	v_add_f32_e32 v72, v108, v72
	v_add_f32_e32 v73, v109, v73
	v_exp_f32_e32 v70, v72
	v_exp_f32_e32 v126, v73
	v_max_f32_e32 v72, v72, v73
	v_max3_f32 v0, v0, v69, v72
	v_pk_add_f32 v[72:73], v[70:71], v[126:127]
	s_nop 0
	v_pk_add_f32 v[72:73], v[72:73], v[72:73] op_sel_hi:[0,1]
	v_cvt_pk_bf16_f32 v69, v70, v126
	s_waitcnt lgkmcnt(3)
	v_mfma_f32_32x32x16_bf16 v[34:49], v[118:121], v[90:93], v[34:49]
	s_waitcnt vmcnt(0)
	v_add_f32_e32 v70, v102, v74
	v_add_f32_e32 v71, v103, v75
	v_exp_f32_e32 v72, v70
	v_exp_f32_e32 v74, v71
	v_max_f32_e32 v71, v70, v71
	v_add_f32_e32 v75, v72, v74
	v_cvt_pk_bf16_f32 v70, v72, v74
	v_add_f32_e32 v76, v104, v76
	v_add_f32_e32 v77, v105, v77
	v_exp_f32_e32 v74, v76
	v_exp_f32_e32 v72, v77
	v_max_f32_e32 v76, v76, v77
	v_max3_f32 v0, v0, v71, v76
	ds_read_b128 v[82:85], v241 offset:17472
	v_pk_add_f32 v[76:77], v[74:75], v[72:73]
	v_cvt_pk_bf16_f32 v71, v74, v72
	v_pk_add_f32 v[94:95], v[76:77], v[76:77] op_sel_hi:[0,1]
	ds_read_b128 v[74:77], v241 offset:22080
	s_waitcnt lgkmcnt(4)
	v_mfma_f32_32x32x16_bf16 v[18:33], v[110:113], v[90:93], v[18:33]
	s_waitcnt lgkmcnt(0)
	v_mfma_f32_32x32x16_bf16 v[18:33], v[74:77], v[66:69], v[18:33]
	ds_read_b128 v[74:77], v241 offset:26720
	v_mfma_f32_32x32x16_bf16 v[2:17], v[86:89], v[90:93], v[2:17]
	v_add_f32_e32 v72, v98, v78
	v_add_f32_e32 v73, v99, v79
	v_exp_f32_e32 v78, v72
	v_exp_f32_e32 v86, v73
	v_max_f32_e32 v98, v72, v73
	v_add_f32_e32 v79, v78, v86
	v_cvt_pk_bf16_f32 v72, v78, v86
	v_add_f32_e32 v73, v100, v80
	v_add_f32_e32 v80, v101, v81
	v_exp_f32_e32 v78, v73
	v_exp_f32_e32 v94, v80
	ds_read_b128 v[86:89], v241 offset:26688
	v_max_f32_e32 v99, v73, v80
	v_pk_add_f32 v[96:97], v[78:79], v[94:95]
	v_cvt_pk_bf16_f32 v73, v78, v94
	ds_read_b128 v[78:81], v241 offset:17504
	v_mfma_f32_32x32x16_bf16 v[34:49], v[82:85], v[66:69], v[34:49]
	ds_read_b128 v[82:85], v241 offset:31296
	v_mfma_f32_32x32x16_bf16 v[50:65], v[114:117], v[90:93], v[50:65]
	ds_read_b128 v[90:93], v241 offset:22112
	s_waitcnt lgkmcnt(3)
	v_mfma_f32_32x32x16_bf16 v[2:17], v[86:89], v[66:69], v[2:17]
	ds_read_b128 v[86:89], v241 offset:31328
	s_waitcnt lgkmcnt(2)
	v_mfma_f32_32x32x16_bf16 v[50:65], v[82:85], v[66:69], v[50:65]
	v_mfma_f32_32x32x16_bf16 v[34:49], v[78:81], v[70:73], v[34:49]
	s_waitcnt lgkmcnt(1)
	v_mfma_f32_32x32x16_bf16 v[18:33], v[90:93], v[70:73], v[18:33]
	v_mfma_f32_32x32x16_bf16 v[2:17], v[74:77], v[70:73], v[2:17]
	s_waitcnt lgkmcnt(0)
	v_mfma_f32_32x32x16_bf16 v[50:65], v[86:89], v[70:73], v[50:65]
	v_max3_f32 v66, v0, v98, v99
	ds_bpermute_b32 v67, v195, v66
	v_add_f32_e32 v0, v96, v97
	s_nop 3
	s_nop 0
	s_waitcnt lgkmcnt(0)
	v_max_f32_e32 v67, v67, v67
	v_max_f32_e32 v67, v66, v67
	v_cmp_lt_f32_e32 vcc, s87, v67
	s_cmp_lg_u64 vcc, 0
	v_add_f32_e32 v0, v240, v0
	s_cselect_b64 s[0:1], -1, 0
.LBB0_97:
	s_andn2_b64 vcc, exec, s[0:1]
	s_cbranch_vccnz .LBB0_99
	v_max_f32_e32 v84, v67, v67
	v_max_f32_e32 v84, 0, v84
	v_exp_f32_e64 v86, -v84
	v_add_f32_e32 v239, v239, v84
	v_mul_f32_e32 v240, v0, v86
	v_pk_mul_f32 v[48:49], v[48:49], v[86:87] op_sel_hi:[1,0]
	v_pk_mul_f32 v[46:47], v[46:47], v[86:87] op_sel_hi:[1,0]
	v_pk_mul_f32 v[44:45], v[44:45], v[86:87] op_sel_hi:[1,0]
	v_pk_mul_f32 v[42:43], v[42:43], v[86:87] op_sel_hi:[1,0]
	v_pk_mul_f32 v[40:41], v[40:41], v[86:87] op_sel_hi:[1,0]
	v_pk_mul_f32 v[38:39], v[38:39], v[86:87] op_sel_hi:[1,0]
	v_pk_mul_f32 v[36:37], v[36:37], v[86:87] op_sel_hi:[1,0]
	v_pk_mul_f32 v[34:35], v[34:35], v[86:87] op_sel_hi:[1,0]
	v_pk_mul_f32 v[32:33], v[32:33], v[86:87] op_sel_hi:[1,0]
	v_pk_mul_f32 v[30:31], v[30:31], v[86:87] op_sel_hi:[1,0]
	v_pk_mul_f32 v[28:29], v[28:29], v[86:87] op_sel_hi:[1,0]
	v_pk_mul_f32 v[26:27], v[26:27], v[86:87] op_sel_hi:[1,0]
	v_pk_mul_f32 v[24:25], v[24:25], v[86:87] op_sel_hi:[1,0]
	v_pk_mul_f32 v[22:23], v[22:23], v[86:87] op_sel_hi:[1,0]
	v_pk_mul_f32 v[20:21], v[20:21], v[86:87] op_sel_hi:[1,0]
	v_pk_mul_f32 v[18:19], v[18:19], v[86:87] op_sel_hi:[1,0]
	v_pk_mul_f32 v[16:17], v[16:17], v[86:87] op_sel_hi:[1,0]
	v_pk_mul_f32 v[14:15], v[14:15], v[86:87] op_sel_hi:[1,0]
	v_pk_mul_f32 v[12:13], v[12:13], v[86:87] op_sel_hi:[1,0]
	v_pk_mul_f32 v[10:11], v[10:11], v[86:87] op_sel_hi:[1,0]
	v_pk_mul_f32 v[8:9], v[8:9], v[86:87] op_sel_hi:[1,0]
	v_pk_mul_f32 v[6:7], v[6:7], v[86:87] op_sel_hi:[1,0]
	v_pk_mul_f32 v[4:5], v[4:5], v[86:87] op_sel_hi:[1,0]
	v_pk_mul_f32 v[2:3], v[2:3], v[86:87] op_sel_hi:[1,0]
	v_pk_mul_f32 v[64:65], v[64:65], v[86:87] op_sel_hi:[1,0]
	v_pk_mul_f32 v[62:63], v[62:63], v[86:87] op_sel_hi:[1,0]
	v_pk_mul_f32 v[60:61], v[60:61], v[86:87] op_sel_hi:[1,0]
	v_pk_mul_f32 v[58:59], v[58:59], v[86:87] op_sel_hi:[1,0]
	v_pk_mul_f32 v[56:57], v[56:57], v[86:87] op_sel_hi:[1,0]
	v_pk_mul_f32 v[54:55], v[54:55], v[86:87] op_sel_hi:[1,0]
	v_pk_mul_f32 v[52:53], v[52:53], v[86:87] op_sel_hi:[1,0]
	v_pk_mul_f32 v[50:51], v[50:51], v[86:87] op_sel_hi:[1,0]
	s_andn2_b64 vcc, exec, s[40:41]
	s_xor_b32 s44, s44, 1
	s_cbranch_vccnz .LBB0_90
	s_branch .LBB0_100
.LBB0_99:
	v_mov_b32_e32 v240, v0
	s_andn2_b64 vcc, exec, s[40:41]
	s_xor_b32 s44, s44, 1
	s_cbranch_vccnz .LBB0_90
